# k4 plus saddr-form LDS-DMA loads in P3/P4/P8 GEMM mainloops
# baseline (speedup 1.0000x reference)
; #define PG8_STAGE(bufoff, gbase, voff) do { _Pragma("unroll") for (int _i = 0; _i < 2; ++_i) \
;         __builtin_amdgcn_global_load_lds((const unsigned*)((const char*)(gbase) + (voff)[_i]), (LAS unsigned*)(lds + (bufoff) + ldsw + _i * 8192), 16, 0, 0); } while (0)
; #define PG8_LDA(dst, b, h) do { _Pragma("unroll") for (int m = 0; m < 4; ++m) _Pragma("unroll") for (int k = 0; k < 2; ++k) dst[m][k] = *(const LAS bf16x8*)(lds + PG8_SA(b, h) + aoff + m * 2048 + k * 1024); } while (0)
; #define PG8_LDB(dst, b, h) do { _Pragma("unroll") for (int n = 0; n < 2; ++n) _Pragma("unroll") for (int k = 0; k < 2; ++k) dst[n][k] = *(const LAS bf16x8*)(lds + PG8_SB(b, h) + boff + n * 2048 + k * 1024); } while (0)
; #define PG8_MMA(ai, bj, At, Bt) do { __builtin_amdgcn_s_setprio(1); _Pragma("unroll") for (int m = 0; m < 4; ++m) _Pragma("unroll") for (int n = 0; n < 2; ++n) _Pragma("unroll") for (int k = 0; k < 2; ++k) \
;         acc[ai][bj][m][n] = __builtin_amdgcn_mfma_f32_16x16x32_bf16(Bt[n][k], At[m][k], acc[ai][bj][m][n], 0, 0, 0); __builtin_amdgcn_s_setprio(0); } while (0)
; #define PG8_WAIT_V(n) asm volatile("s_waitcnt vmcnt(" #n ")" ::: "memory")
; #define PG8_WAIT_L(n) asm volatile("s_waitcnt lgkmcnt(" #n ")" ::: "memory")
; #define PG8_BAR __builtin_amdgcn_s_barrier()
; #define PG8_SCHED __builtin_amdgcn_sched_barrier(0)
; template <class Epi, class Sched>
; __device__ __forceinline__ void gemm_phase(LAS unsigned char* lds, const Gemm g, const Sched& S, const Epi& E) {
;     ...
;         for (int t = 0; t < nt; t += 2) {
;             const bool last = (t == nt - 2);
;             const char* a1 = cA + (size_t)(t + 1) * kstep;
;             const char* a2 = last ? nA : cA + (size_t)(t + 2) * kstep; const char* b2 = last ? nB : cB + (size_t)(t + 2) * kstep;
;             const char* a3 = a2 + kstep; const char* b3 = b2 + kstep;
;             PG8_LDB(B0, 0, 0); PG8_LDB(B1, 0, 1); PG8_SCHED; PG8_LDA(At, 0, 0); PG8_STAGE(PG8_SA(1, 1), a1 + hstepA, voffA);
;             PG8_WAIT_V(8); PG8_WAIT_L(0); PG8_BAR; PG8_MMA(0, 0, At, B0); PG8_MMA(0, 1, At, B1); PG8_BAR; PG8_SCHED;
;             PG8_LDA(At, 0, 1); PG8_STAGE(PG8_SB(0, 0), b2, voffB); PG8_STAGE(PG8_SB(0, 1), b2 + hstepB, voffB); PG8_STAGE(PG8_SA(0, 0), a2, voffA);
;             PG8_WAIT_V(8); PG8_WAIT_L(0); PG8_BAR; PG8_MMA(1, 0, At, B0); PG8_MMA(1, 1, At, B1); PG8_BAR; PG8_SCHED;
.LBB0_497:
	ds_read_b128 v[146:149], v153
	ds_read_b128 v[156:159], v153 offset:1024
	ds_read_b128 v[160:163], v153 offset:2048
	ds_read_b128 v[164:167], v153 offset:3072
	ds_read_b128 v[168:171], v154
	ds_read_b128 v[172:175], v154 offset:1024
	ds_read_b128 v[176:179], v154 offset:2048
	ds_read_b128 v[180:183], v154 offset:3072
	s_add_u32 s2, s56, 0xfff80080
	s_addc_u32 s3, s57, -1
	s_cmp_eq_u32 s77, 28
	s_cselect_b32 s65, s30, s3
	s_cselect_b32 s64, s31, s2
	s_cselect_b32 s61, s37, s76
	s_cselect_b32 s60, s39, s51
	s_add_i32 m0, s34, 0xc000
	ds_read_b128 v[184:187], v155
	ds_read_b128 v[192:195], v155 offset:1024
	ds_read_b128 v[196:199], v155 offset:2048
	ds_read_b128 v[200:203], v155 offset:3072
	ds_read_b128 v[204:207], v155 offset:4096
	ds_read_b128 v[208:211], v155 offset:5120
	ds_read_b128 v[212:215], v155 offset:6144
	ds_read_b128 v[216:219], v155 offset:7168
	global_load_lds_dwordx4 v138, s[56:57]
	s_add_i32 m0, s34, 0xe000
	s_nop 0
	global_load_lds_dwordx4 v140, s[56:57]
	s_waitcnt vmcnt(8)
	s_waitcnt lgkmcnt(0)
	s_barrier
	s_setprio 1
	s_waitcnt lgkmcnt(0)
	v_mfma_f32_16x16x32_bf16 v[124:127], v[146:149], v[184:187], v[124:127]
	v_mfma_f32_16x16x32_bf16 v[120:123], v[160:163], v[184:187], v[120:123]
	v_mfma_f32_16x16x32_bf16 v[108:111], v[146:149], v[196:199], v[108:111]
	v_mfma_f32_16x16x32_bf16 v[104:107], v[160:163], v[196:199], v[104:107]
	v_mfma_f32_16x16x32_bf16 v[92:95], v[146:149], v[204:207], v[92:95]
	v_mfma_f32_16x16x32_bf16 v[88:91], v[160:163], v[204:207], v[88:91]
	v_mfma_f32_16x16x32_bf16 v[76:79], v[146:149], v[212:215], v[76:79]
	v_mfma_f32_16x16x32_bf16 v[72:75], v[160:163], v[212:215], v[72:75]
	v_mfma_f32_16x16x32_bf16 v[124:127], v[156:159], v[192:195], v[124:127]
	v_mfma_f32_16x16x32_bf16 v[120:123], v[164:167], v[192:195], v[120:123]
	v_mfma_f32_16x16x32_bf16 v[108:111], v[156:159], v[200:203], v[108:111]
	v_mfma_f32_16x16x32_bf16 v[104:107], v[164:167], v[200:203], v[104:107]
	v_mfma_f32_16x16x32_bf16 v[92:95], v[156:159], v[208:211], v[92:95]
	v_mfma_f32_16x16x32_bf16 v[88:91], v[164:167], v[208:211], v[88:91]
	v_mfma_f32_16x16x32_bf16 v[76:79], v[156:159], v[216:219], v[76:79]
	v_mfma_f32_16x16x32_bf16 v[72:75], v[164:167], v[216:219], v[72:75]
	s_setprio 0
	s_setprio 1
	v_mfma_f32_16x16x32_bf16 v[116:119], v[168:171], v[184:187], v[116:119]
	v_mfma_f32_16x16x32_bf16 v[112:115], v[176:179], v[184:187], v[112:115]
	v_mfma_f32_16x16x32_bf16 v[100:103], v[168:171], v[196:199], v[100:103]
	v_mfma_f32_16x16x32_bf16 v[96:99], v[176:179], v[196:199], v[96:99]
	v_mfma_f32_16x16x32_bf16 v[84:87], v[168:171], v[204:207], v[84:87]
	v_mfma_f32_16x16x32_bf16 v[80:83], v[176:179], v[204:207], v[80:83]
	v_mfma_f32_16x16x32_bf16 v[68:71], v[168:171], v[212:215], v[68:71]
	v_mfma_f32_16x16x32_bf16 v[64:67], v[176:179], v[212:215], v[64:67]
	v_mfma_f32_16x16x32_bf16 v[116:119], v[172:175], v[192:195], v[116:119]
	v_mfma_f32_16x16x32_bf16 v[112:115], v[180:183], v[192:195], v[112:115]
	v_mfma_f32_16x16x32_bf16 v[100:103], v[172:175], v[200:203], v[100:103]
	v_mfma_f32_16x16x32_bf16 v[96:99], v[180:183], v[200:203], v[96:99]
	v_mfma_f32_16x16x32_bf16 v[84:87], v[172:175], v[208:211], v[84:87]
	v_mfma_f32_16x16x32_bf16 v[80:83], v[180:183], v[208:211], v[80:83]
	v_mfma_f32_16x16x32_bf16 v[68:71], v[172:175], v[216:219], v[68:71]
	v_mfma_f32_16x16x32_bf16 v[64:67], v[180:183], v[216:219], v[64:67]
	s_setprio 2
	s_barrier
	s_add_i32 s2, s73, s33
	s_mov_b32 m0, s2
	ds_read_b128 v[184:187], v155 offset:16384
	ds_read_b128 v[192:195], v155 offset:17408
	ds_read_b128 v[196:199], v155 offset:18432
	ds_read_b128 v[200:203], v155 offset:19456
	ds_read_b128 v[204:207], v155 offset:20480
	ds_read_b128 v[208:211], v155 offset:21504
	ds_read_b128 v[212:215], v155 offset:22528
	ds_read_b128 v[216:219], v155 offset:23552
	global_load_lds_dwordx4 v130, s[60:61]
	s_add_i32 m0, s2, 0x2000
	s_add_u32 s2, s60, 0x80000
	s_addc_u32 s3, s61, 0
	s_add_i32 s46, s74, s33
	global_load_lds_dwordx4 v134, s[60:61]
	s_mov_b32 m0, s46
	s_nop 0
	global_load_lds_dwordx4 v130, s[2:3]
	s_add_i32 m0, s46, 0x2000
	s_nop 0
	global_load_lds_dwordx4 v134, s[2:3]
	s_mov_b32 m0, s34
	s_nop 0
	global_load_lds_dwordx4 v128, s[64:65]
	s_mov_b32 m0, s35
	s_nop 0
	global_load_lds_dwordx4 v132, s[64:65]
	s_waitcnt vmcnt(8)
	s_waitcnt lgkmcnt(0)
	s_barrier
	s_setprio 1
	s_waitcnt lgkmcnt(0)
	v_mfma_f32_16x16x32_bf16 v[60:63], v[146:149], v[184:187], v[60:63]
	v_mfma_f32_16x16x32_bf16 v[56:59], v[160:163], v[184:187], v[56:59]
	v_mfma_f32_16x16x32_bf16 v[44:47], v[146:149], v[196:199], v[44:47]
	v_mfma_f32_16x16x32_bf16 v[40:43], v[160:163], v[196:199], v[40:43]
	v_mfma_f32_16x16x32_bf16 v[28:31], v[146:149], v[204:207], v[28:31]
	v_mfma_f32_16x16x32_bf16 v[24:27], v[160:163], v[204:207], v[24:27]
	v_mfma_f32_16x16x32_bf16 v[12:15], v[146:149], v[212:215], v[12:15]
	v_mfma_f32_16x16x32_bf16 v[8:11], v[160:163], v[212:215], v[8:11]
	v_mfma_f32_16x16x32_bf16 v[60:63], v[156:159], v[192:195], v[60:63]
	v_mfma_f32_16x16x32_bf16 v[56:59], v[164:167], v[192:195], v[56:59]
	v_mfma_f32_16x16x32_bf16 v[44:47], v[156:159], v[200:203], v[44:47]
	v_mfma_f32_16x16x32_bf16 v[40:43], v[164:167], v[200:203], v[40:43]
	v_mfma_f32_16x16x32_bf16 v[28:31], v[156:159], v[208:211], v[28:31]
	v_mfma_f32_16x16x32_bf16 v[24:27], v[164:167], v[208:211], v[24:27]
	v_mfma_f32_16x16x32_bf16 v[12:15], v[156:159], v[216:219], v[12:15]
	v_mfma_f32_16x16x32_bf16 v[8:11], v[164:167], v[216:219], v[8:11]
	s_setprio 0
	s_setprio 1
	v_mfma_f32_16x16x32_bf16 v[52:55], v[168:171], v[184:187], v[52:55]
	v_mfma_f32_16x16x32_bf16 v[48:51], v[176:179], v[184:187], v[48:51]
	v_mfma_f32_16x16x32_bf16 v[36:39], v[168:171], v[196:199], v[36:39]
	v_mfma_f32_16x16x32_bf16 v[32:35], v[176:179], v[196:199], v[32:35]
	v_mfma_f32_16x16x32_bf16 v[20:23], v[168:171], v[204:207], v[20:23]
	v_mfma_f32_16x16x32_bf16 v[16:19], v[176:179], v[204:207], v[16:19]
	v_mfma_f32_16x16x32_bf16 v[4:7], v[168:171], v[212:215], v[4:7]
	v_mfma_f32_16x16x32_bf16 v[0:3], v[176:179], v[212:215], v[0:3]
	v_mfma_f32_16x16x32_bf16 v[52:55], v[172:175], v[192:195], v[52:55]
	v_mfma_f32_16x16x32_bf16 v[48:51], v[180:183], v[192:195], v[48:51]
	v_mfma_f32_16x16x32_bf16 v[36:39], v[172:175], v[200:203], v[36:39]
	v_mfma_f32_16x16x32_bf16 v[32:35], v[180:183], v[200:203], v[32:35]
	v_mfma_f32_16x16x32_bf16 v[20:23], v[172:175], v[208:211], v[20:23]
	v_mfma_f32_16x16x32_bf16 v[16:19], v[180:183], v[208:211], v[16:19]
	v_mfma_f32_16x16x32_bf16 v[4:7], v[172:175], v[216:219], v[4:7]
	v_mfma_f32_16x16x32_bf16 v[0:3], v[180:183], v[216:219], v[0:3]
	s_setprio 2
	s_barrier
; #define PG8_STAGE(bufoff, gbase, voff) do { _Pragma("unroll") for (int _i = 0; _i < 2; ++_i) \
;         __builtin_amdgcn_global_load_lds((const unsigned*)((const char*)(gbase) + (voff)[_i]), (LAS unsigned*)(lds + (bufoff) + ldsw + _i * 8192), 16, 0, 0); } while (0)
; #define PG8_LDA(dst, b, h) do { _Pragma("unroll") for (int m = 0; m < 4; ++m) _Pragma("unroll") for (int k = 0; k < 2; ++k) dst[m][k] = *(const LAS bf16x8*)(lds + PG8_SA(b, h) + aoff + m * 2048 + k * 1024); } while (0)
; #define PG8_LDB(dst, b, h) do { _Pragma("unroll") for (int n = 0; n < 2; ++n) _Pragma("unroll") for (int k = 0; k < 2; ++k) dst[n][k] = *(const LAS bf16x8*)(lds + PG8_SB(b, h) + boff + n * 2048 + k * 1024); } while (0)
; #define PG8_MMA(ai, bj, At, Bt) do { __builtin_amdgcn_s_setprio(1); _Pragma("unroll") for (int m = 0; m < 4; ++m) _Pragma("unroll") for (int n = 0; n < 2; ++n) _Pragma("unroll") for (int k = 0; k < 2; ++k) \
;         acc[ai][bj][m][n] = __builtin_amdgcn_mfma_f32_16x16x32_bf16(Bt[n][k], At[m][k], acc[ai][bj][m][n], 0, 0, 0); __builtin_amdgcn_s_setprio(0); } while (0)
; #define PG8_WAIT_V(n) asm volatile("s_waitcnt vmcnt(" #n ")" ::: "memory")
; #define PG8_WAIT_L(n) asm volatile("s_waitcnt lgkmcnt(" #n ")" ::: "memory")
; #define PG8_BAR __builtin_amdgcn_s_barrier()
; #define PG8_SCHED __builtin_amdgcn_sched_barrier(0)
; template <class Epi, class Sched>
; __device__ __forceinline__ void gemm_phase(LAS unsigned char* lds, const Gemm g, const Sched& S, const Epi& E) {
;     ...
;             PG8_LDB(B0, 1, 0); PG8_LDB(B1, 1, 1); PG8_SCHED; PG8_LDA(At, 1, 0); PG8_STAGE(PG8_SA(0, 1), a2 + hstepA, voffA);
;             PG8_WAIT_V(8); PG8_WAIT_L(0); PG8_BAR; PG8_MMA(0, 0, At, B0); PG8_MMA(0, 1, At, B1); PG8_BAR; PG8_SCHED;
;             PG8_LDA(At, 1, 1); PG8_STAGE(PG8_SB(1, 0), b3, voffB); PG8_STAGE(PG8_SB(1, 1), b3 + hstepB, voffB); PG8_STAGE(PG8_SA(1, 0), a3, voffA);
;             PG8_WAIT_V(8); PG8_WAIT_L(0); PG8_BAR; PG8_MMA(1, 0, At, B0); PG8_MMA(1, 1, At, B1); PG8_BAR; PG8_SCHED;
;         }
;         if (wr == 0) PG8_BAR;
	s_add_i32 s46, 0, 0x18000
	s_add_i32 s47, 0, 0x1c000
	v_add_u32_e32 v164, s46, v152
	v_add_u32_e32 v180, s47, v152
	ds_read_b128 v[146:149], v164
	ds_read_b128 v[156:159], v164 offset:1024
	ds_read_b128 v[160:163], v164 offset:2048
	ds_read_b128 v[164:167], v164 offset:3072
	ds_read_b128 v[168:171], v180
	ds_read_b128 v[172:175], v180 offset:1024
	ds_read_b128 v[176:179], v180 offset:2048
	ds_read_b128 v[180:183], v180 offset:3072
	s_add_u32 s2, s64, 0x80000
	s_addc_u32 s3, s65, 0
	s_mov_b32 m0, s66
	ds_read_b128 v[184:187], v155 offset:32768
	ds_read_b128 v[192:195], v155 offset:33792
	ds_read_b128 v[196:199], v155 offset:34816
	ds_read_b128 v[200:203], v155 offset:35840
	ds_read_b128 v[204:207], v155 offset:36864
	ds_read_b128 v[208:211], v155 offset:37888
	ds_read_b128 v[212:215], v155 offset:38912
	ds_read_b128 v[216:219], v155 offset:39936
	global_load_lds_dwordx4 v128, s[2:3]
	s_mov_b32 m0, s67
	s_nop 0
	global_load_lds_dwordx4 v132, s[2:3]
	s_waitcnt vmcnt(8)
	s_waitcnt lgkmcnt(0)
	s_barrier
	s_setprio 1
	s_waitcnt lgkmcnt(0)
	v_mfma_f32_16x16x32_bf16 v[124:127], v[146:149], v[184:187], v[124:127]
	v_mfma_f32_16x16x32_bf16 v[120:123], v[160:163], v[184:187], v[120:123]
	v_mfma_f32_16x16x32_bf16 v[108:111], v[146:149], v[196:199], v[108:111]
	v_mfma_f32_16x16x32_bf16 v[104:107], v[160:163], v[196:199], v[104:107]
	v_mfma_f32_16x16x32_bf16 v[92:95], v[146:149], v[204:207], v[92:95]
	v_mfma_f32_16x16x32_bf16 v[88:91], v[160:163], v[204:207], v[88:91]
	v_mfma_f32_16x16x32_bf16 v[76:79], v[146:149], v[212:215], v[76:79]
	v_mfma_f32_16x16x32_bf16 v[72:75], v[160:163], v[212:215], v[72:75]
	v_mfma_f32_16x16x32_bf16 v[124:127], v[156:159], v[192:195], v[124:127]
	v_mfma_f32_16x16x32_bf16 v[120:123], v[164:167], v[192:195], v[120:123]
	v_mfma_f32_16x16x32_bf16 v[108:111], v[156:159], v[200:203], v[108:111]
	v_mfma_f32_16x16x32_bf16 v[104:107], v[164:167], v[200:203], v[104:107]
	v_mfma_f32_16x16x32_bf16 v[92:95], v[156:159], v[208:211], v[92:95]
	v_mfma_f32_16x16x32_bf16 v[88:91], v[164:167], v[208:211], v[88:91]
	v_mfma_f32_16x16x32_bf16 v[76:79], v[156:159], v[216:219], v[76:79]
	v_mfma_f32_16x16x32_bf16 v[72:75], v[164:167], v[216:219], v[72:75]
	s_setprio 0
	s_setprio 1
	v_mfma_f32_16x16x32_bf16 v[116:119], v[168:171], v[184:187], v[116:119]
	v_mfma_f32_16x16x32_bf16 v[112:115], v[176:179], v[184:187], v[112:115]
	v_mfma_f32_16x16x32_bf16 v[100:103], v[168:171], v[196:199], v[100:103]
	v_mfma_f32_16x16x32_bf16 v[96:99], v[176:179], v[196:199], v[96:99]
	v_mfma_f32_16x16x32_bf16 v[84:87], v[168:171], v[204:207], v[84:87]
	v_mfma_f32_16x16x32_bf16 v[80:83], v[176:179], v[204:207], v[80:83]
	v_mfma_f32_16x16x32_bf16 v[68:71], v[168:171], v[212:215], v[68:71]
	v_mfma_f32_16x16x32_bf16 v[64:67], v[176:179], v[212:215], v[64:67]
	v_mfma_f32_16x16x32_bf16 v[116:119], v[172:175], v[192:195], v[116:119]
	v_mfma_f32_16x16x32_bf16 v[112:115], v[180:183], v[192:195], v[112:115]
	v_mfma_f32_16x16x32_bf16 v[100:103], v[172:175], v[200:203], v[100:103]
	v_mfma_f32_16x16x32_bf16 v[96:99], v[180:183], v[200:203], v[96:99]
	v_mfma_f32_16x16x32_bf16 v[84:87], v[172:175], v[208:211], v[84:87]
	v_mfma_f32_16x16x32_bf16 v[80:83], v[180:183], v[208:211], v[80:83]
	v_mfma_f32_16x16x32_bf16 v[68:71], v[172:175], v[216:219], v[68:71]
	v_mfma_f32_16x16x32_bf16 v[64:67], v[180:183], v[216:219], v[64:67]
	s_setprio 2
	s_barrier
	s_add_i32 s2, s46, s33
	s_add_i32 m0, s2, 0xffffff80
	ds_read_b128 v[184:187], v155 offset:49152
	ds_read_b128 v[192:195], v155 offset:50176
	ds_read_b128 v[196:199], v155 offset:51200
	ds_read_b128 v[200:203], v155 offset:52224
	ds_read_b128 v[204:207], v155 offset:53248
	ds_read_b128 v[208:211], v155 offset:54272
	ds_read_b128 v[212:215], v155 offset:55296
	ds_read_b128 v[216:219], v155 offset:56320
	global_load_lds_dwordx4 v130, s[60:61] offset:128
	s_add_i32 m0, s2, 0x1f80
	s_add_u32 s2, s60, 0x80080
	s_addc_u32 s3, s61, 0
	s_add_i32 s46, s47, s33
	global_load_lds_dwordx4 v134, s[60:61] offset:128
	s_mov_b32 m0, s46
	s_nop 0
	global_load_lds_dwordx4 v130, s[2:3]
	s_add_i32 m0, s46, 0x2000
	s_nop 0
	global_load_lds_dwordx4 v134, s[2:3]
	s_add_i32 m0, s71, 0xffffff80
	s_nop 0
	global_load_lds_dwordx4 v128, s[64:65] offset:128
	s_add_i32 m0, s72, 0xffffff80
	s_nop 0
	global_load_lds_dwordx4 v132, s[64:65] offset:128
	s_waitcnt vmcnt(8)
	s_waitcnt lgkmcnt(0)
	s_barrier
	s_setprio 1
	s_waitcnt lgkmcnt(0)
	v_mfma_f32_16x16x32_bf16 v[60:63], v[146:149], v[184:187], v[60:63]
	v_mfma_f32_16x16x32_bf16 v[56:59], v[160:163], v[184:187], v[56:59]
	v_mfma_f32_16x16x32_bf16 v[44:47], v[146:149], v[196:199], v[44:47]
	v_mfma_f32_16x16x32_bf16 v[40:43], v[160:163], v[196:199], v[40:43]
	v_mfma_f32_16x16x32_bf16 v[28:31], v[146:149], v[204:207], v[28:31]
	v_mfma_f32_16x16x32_bf16 v[24:27], v[160:163], v[204:207], v[24:27]
	v_mfma_f32_16x16x32_bf16 v[12:15], v[146:149], v[212:215], v[12:15]
	v_mfma_f32_16x16x32_bf16 v[8:11], v[160:163], v[212:215], v[8:11]
	v_mfma_f32_16x16x32_bf16 v[60:63], v[156:159], v[192:195], v[60:63]
	v_mfma_f32_16x16x32_bf16 v[56:59], v[164:167], v[192:195], v[56:59]
	v_mfma_f32_16x16x32_bf16 v[44:47], v[156:159], v[200:203], v[44:47]
	v_mfma_f32_16x16x32_bf16 v[40:43], v[164:167], v[200:203], v[40:43]
	v_mfma_f32_16x16x32_bf16 v[28:31], v[156:159], v[208:211], v[28:31]
	v_mfma_f32_16x16x32_bf16 v[24:27], v[164:167], v[208:211], v[24:27]
	v_mfma_f32_16x16x32_bf16 v[12:15], v[156:159], v[216:219], v[12:15]
	v_mfma_f32_16x16x32_bf16 v[8:11], v[164:167], v[216:219], v[8:11]
	s_setprio 0
	s_setprio 1
	v_mfma_f32_16x16x32_bf16 v[52:55], v[168:171], v[184:187], v[52:55]
	v_mfma_f32_16x16x32_bf16 v[48:51], v[176:179], v[184:187], v[48:51]
	v_mfma_f32_16x16x32_bf16 v[36:39], v[168:171], v[196:199], v[36:39]
	v_mfma_f32_16x16x32_bf16 v[32:35], v[176:179], v[196:199], v[32:35]
	v_mfma_f32_16x16x32_bf16 v[20:23], v[168:171], v[204:207], v[20:23]
	v_mfma_f32_16x16x32_bf16 v[16:19], v[176:179], v[204:207], v[16:19]
	v_mfma_f32_16x16x32_bf16 v[4:7], v[168:171], v[212:215], v[4:7]
	v_mfma_f32_16x16x32_bf16 v[0:3], v[176:179], v[212:215], v[0:3]
	v_mfma_f32_16x16x32_bf16 v[52:55], v[172:175], v[192:195], v[52:55]
	v_mfma_f32_16x16x32_bf16 v[48:51], v[180:183], v[192:195], v[48:51]
	v_mfma_f32_16x16x32_bf16 v[36:39], v[172:175], v[200:203], v[36:39]
	v_mfma_f32_16x16x32_bf16 v[32:35], v[180:183], v[200:203], v[32:35]
	v_mfma_f32_16x16x32_bf16 v[20:23], v[172:175], v[208:211], v[20:23]
	v_mfma_f32_16x16x32_bf16 v[16:19], v[180:183], v[208:211], v[16:19]
	v_mfma_f32_16x16x32_bf16 v[4:7], v[172:175], v[216:219], v[4:7]
	v_mfma_f32_16x16x32_bf16 v[0:3], v[180:183], v[216:219], v[0:3]
	s_setprio 2
	s_barrier
	s_add_i32 s77, s77, 2
	s_add_u32 s56, s56, 0x100
	s_addc_u32 s57, s57, 0
	s_add_u32 s51, s51, 0x100
	s_addc_u32 s76, s76, 0
	s_cmp_gt_u32 s77, 29
	s_cbranch_scc0 .LBB0_497
	s_and_b64 vcc, exec, s[16:17]
	s_cbranch_vccz .LBB0_500
	s_barrier

; #define PG8_STAGE(bufoff, gbase, voff) do { _Pragma("unroll") for (int _i = 0; _i < 2; ++_i) \
;         __builtin_amdgcn_global_load_lds((const unsigned*)((const char*)(gbase) + (voff)[_i]), (LAS unsigned*)(lds + (bufoff) + ldsw + _i * 8192), 16, 0, 0); } while (0)
; #define PG8_LDA(dst, b, h) do { _Pragma("unroll") for (int m = 0; m < 4; ++m) _Pragma("unroll") for (int k = 0; k < 2; ++k) dst[m][k] = *(const LAS bf16x8*)(lds + PG8_SA(b, h) + aoff + m * 2048 + k * 1024); } while (0)
; #define PG8_LDB(dst, b, h) do { _Pragma("unroll") for (int n = 0; n < 2; ++n) _Pragma("unroll") for (int k = 0; k < 2; ++k) dst[n][k] = *(const LAS bf16x8*)(lds + PG8_SB(b, h) + boff + n * 2048 + k * 1024); } while (0)
; #define PG8_MMA(ai, bj, At, Bt) do { __builtin_amdgcn_s_setprio(1); _Pragma("unroll") for (int m = 0; m < 4; ++m) _Pragma("unroll") for (int n = 0; n < 2; ++n) _Pragma("unroll") for (int k = 0; k < 2; ++k) \
;         acc[ai][bj][m][n] = __builtin_amdgcn_mfma_f32_16x16x32_bf16(Bt[n][k], At[m][k], acc[ai][bj][m][n], 0, 0, 0); __builtin_amdgcn_s_setprio(0); } while (0)
; #define PG8_WAIT_V(n) asm volatile("s_waitcnt vmcnt(" #n ")" ::: "memory")
; #define PG8_WAIT_L(n) asm volatile("s_waitcnt lgkmcnt(" #n ")" ::: "memory")
; #define PG8_BAR __builtin_amdgcn_s_barrier()
; #define PG8_SCHED __builtin_amdgcn_sched_barrier(0)
; template <class Epi, class Sched>
; __device__ __forceinline__ void gemm_phase(LAS unsigned char* lds, const Gemm g, const Sched& S, const Epi& E) {
;     ...
;         for (int t = 0; t < nt; t += 2) {
;             const bool last = (t == nt - 2);
;             const char* a1 = cA + (size_t)(t + 1) * kstep;
;             const char* a2 = last ? nA : cA + (size_t)(t + 2) * kstep; const char* b2 = last ? nB : cB + (size_t)(t + 2) * kstep;
;             const char* a3 = a2 + kstep; const char* b3 = b2 + kstep;
;             PG8_LDB(B0, 0, 0); PG8_LDB(B1, 0, 1); PG8_SCHED; PG8_LDA(At, 0, 0); PG8_STAGE(PG8_SA(1, 1), a1 + hstepA, voffA);
;             PG8_WAIT_V(8); PG8_WAIT_L(0); PG8_BAR; PG8_MMA(0, 0, At, B0); PG8_MMA(0, 1, At, B1); PG8_BAR; PG8_SCHED;
;             PG8_LDA(At, 0, 1); PG8_STAGE(PG8_SB(0, 0), b2, voffB); PG8_STAGE(PG8_SB(0, 1), b2 + hstepB, voffB); PG8_STAGE(PG8_SA(0, 0), a2, voffA);
;             PG8_WAIT_V(8); PG8_WAIT_L(0); PG8_BAR; PG8_MMA(1, 0, At, B0); PG8_MMA(1, 1, At, B1); PG8_BAR; PG8_SCHED;
.LBB0_588:
	ds_read_b128 v[146:149], v154
	ds_read_b128 v[158:161], v154 offset:1024
	ds_read_b128 v[162:165], v154 offset:2048
	ds_read_b128 v[166:169], v154 offset:3072
	ds_read_b128 v[170:173], v155
	ds_read_b128 v[174:177], v155 offset:1024
	ds_read_b128 v[178:181], v155 offset:2048
	ds_read_b128 v[182:185], v155 offset:3072
	s_add_u32 s2, s50, 0xfff80080
	s_addc_u32 s3, s51, -1
	s_cmp_eq_u32 s77, 28
	s_cselect_b32 s61, s7, s3
	s_cselect_b32 s60, s30, s2
	s_cselect_b32 s57, s31, s76
	s_cselect_b32 s56, s37, s39
	s_add_i32 m0, s34, 0xc000
	ds_read_b128 v[190:193], v156
	ds_read_b128 v[194:197], v156 offset:1024
	ds_read_b128 v[198:201], v156 offset:2048
	ds_read_b128 v[202:205], v156 offset:3072
	ds_read_b128 v[206:209], v156 offset:4096
	ds_read_b128 v[210:213], v156 offset:5120
	ds_read_b128 v[214:217], v156 offset:6144
	ds_read_b128 v[218:221], v156 offset:7168
	global_load_lds_dwordx4 v138, s[50:51]
	s_add_i32 m0, s34, 0xe000
	s_nop 0
	global_load_lds_dwordx4 v140, s[50:51]
	s_waitcnt vmcnt(8)
	s_waitcnt lgkmcnt(0)
	s_barrier
	s_setprio 1
	s_waitcnt lgkmcnt(0)
	v_mfma_f32_16x16x32_bf16 v[124:127], v[146:149], v[190:193], v[124:127]
	v_mfma_f32_16x16x32_bf16 v[120:123], v[162:165], v[190:193], v[120:123]
	v_mfma_f32_16x16x32_bf16 v[108:111], v[146:149], v[198:201], v[108:111]
	v_mfma_f32_16x16x32_bf16 v[104:107], v[162:165], v[198:201], v[104:107]
	v_mfma_f32_16x16x32_bf16 v[92:95], v[146:149], v[206:209], v[92:95]
	v_mfma_f32_16x16x32_bf16 v[88:91], v[162:165], v[206:209], v[88:91]
	v_mfma_f32_16x16x32_bf16 v[76:79], v[146:149], v[214:217], v[76:79]
	v_mfma_f32_16x16x32_bf16 v[72:75], v[162:165], v[214:217], v[72:75]
	v_mfma_f32_16x16x32_bf16 v[124:127], v[158:161], v[194:197], v[124:127]
	v_mfma_f32_16x16x32_bf16 v[120:123], v[166:169], v[194:197], v[120:123]
	v_mfma_f32_16x16x32_bf16 v[108:111], v[158:161], v[202:205], v[108:111]
	v_mfma_f32_16x16x32_bf16 v[104:107], v[166:169], v[202:205], v[104:107]
	v_mfma_f32_16x16x32_bf16 v[92:95], v[158:161], v[210:213], v[92:95]
	v_mfma_f32_16x16x32_bf16 v[88:91], v[166:169], v[210:213], v[88:91]
	v_mfma_f32_16x16x32_bf16 v[76:79], v[158:161], v[218:221], v[76:79]
	v_mfma_f32_16x16x32_bf16 v[72:75], v[166:169], v[218:221], v[72:75]
	s_setprio 0
	s_setprio 1
	v_mfma_f32_16x16x32_bf16 v[116:119], v[170:173], v[190:193], v[116:119]
	v_mfma_f32_16x16x32_bf16 v[112:115], v[178:181], v[190:193], v[112:115]
	v_mfma_f32_16x16x32_bf16 v[100:103], v[170:173], v[198:201], v[100:103]
	v_mfma_f32_16x16x32_bf16 v[96:99], v[178:181], v[198:201], v[96:99]
	v_mfma_f32_16x16x32_bf16 v[84:87], v[170:173], v[206:209], v[84:87]
	v_mfma_f32_16x16x32_bf16 v[80:83], v[178:181], v[206:209], v[80:83]
	v_mfma_f32_16x16x32_bf16 v[68:71], v[170:173], v[214:217], v[68:71]
	v_mfma_f32_16x16x32_bf16 v[64:67], v[178:181], v[214:217], v[64:67]
	v_mfma_f32_16x16x32_bf16 v[116:119], v[174:177], v[194:197], v[116:119]
	v_mfma_f32_16x16x32_bf16 v[112:115], v[182:185], v[194:197], v[112:115]
	v_mfma_f32_16x16x32_bf16 v[100:103], v[174:177], v[202:205], v[100:103]
	v_mfma_f32_16x16x32_bf16 v[96:99], v[182:185], v[202:205], v[96:99]
	v_mfma_f32_16x16x32_bf16 v[84:87], v[174:177], v[210:213], v[84:87]
	v_mfma_f32_16x16x32_bf16 v[80:83], v[182:185], v[210:213], v[80:83]
	v_mfma_f32_16x16x32_bf16 v[68:71], v[174:177], v[218:221], v[68:71]
	v_mfma_f32_16x16x32_bf16 v[64:67], v[182:185], v[218:221], v[64:67]
	s_setprio 2
	s_barrier
	s_add_i32 s2, s69, s33
	s_mov_b32 m0, s2
	ds_read_b128 v[190:193], v156 offset:16384
	ds_read_b128 v[194:197], v156 offset:17408
	ds_read_b128 v[198:201], v156 offset:18432
	ds_read_b128 v[202:205], v156 offset:19456
	ds_read_b128 v[206:209], v156 offset:20480
	ds_read_b128 v[210:213], v156 offset:21504
	ds_read_b128 v[214:217], v156 offset:22528
	ds_read_b128 v[218:221], v156 offset:23552
	global_load_lds_dwordx4 v130, s[56:57]
	s_add_i32 m0, s2, 0x2000
	s_add_u32 s2, s56, 0x80000
	s_addc_u32 s3, s57, 0
	s_add_i32 s46, s70, s33
	global_load_lds_dwordx4 v134, s[56:57]
	s_mov_b32 m0, s46
	s_nop 0
	global_load_lds_dwordx4 v130, s[2:3]
	s_add_i32 m0, s46, 0x2000
	s_nop 0
	global_load_lds_dwordx4 v134, s[2:3]
	s_mov_b32 m0, s34
	s_nop 0
	global_load_lds_dwordx4 v128, s[60:61]
	s_mov_b32 m0, s35
	s_nop 0
	global_load_lds_dwordx4 v132, s[60:61]
	s_waitcnt vmcnt(8)
	s_waitcnt lgkmcnt(0)
	s_barrier
	s_setprio 1
	s_waitcnt lgkmcnt(0)
	v_mfma_f32_16x16x32_bf16 v[60:63], v[146:149], v[190:193], v[60:63]
	v_mfma_f32_16x16x32_bf16 v[56:59], v[162:165], v[190:193], v[56:59]
	v_mfma_f32_16x16x32_bf16 v[44:47], v[146:149], v[198:201], v[44:47]
	v_mfma_f32_16x16x32_bf16 v[40:43], v[162:165], v[198:201], v[40:43]
	v_mfma_f32_16x16x32_bf16 v[28:31], v[146:149], v[206:209], v[28:31]
	v_mfma_f32_16x16x32_bf16 v[24:27], v[162:165], v[206:209], v[24:27]
	v_mfma_f32_16x16x32_bf16 v[12:15], v[146:149], v[214:217], v[12:15]
	v_mfma_f32_16x16x32_bf16 v[8:11], v[162:165], v[214:217], v[8:11]
	v_mfma_f32_16x16x32_bf16 v[60:63], v[158:161], v[194:197], v[60:63]
	v_mfma_f32_16x16x32_bf16 v[56:59], v[166:169], v[194:197], v[56:59]
	v_mfma_f32_16x16x32_bf16 v[44:47], v[158:161], v[202:205], v[44:47]
	v_mfma_f32_16x16x32_bf16 v[40:43], v[166:169], v[202:205], v[40:43]
	v_mfma_f32_16x16x32_bf16 v[28:31], v[158:161], v[210:213], v[28:31]
	v_mfma_f32_16x16x32_bf16 v[24:27], v[166:169], v[210:213], v[24:27]
	v_mfma_f32_16x16x32_bf16 v[12:15], v[158:161], v[218:221], v[12:15]
	v_mfma_f32_16x16x32_bf16 v[8:11], v[166:169], v[218:221], v[8:11]
	s_setprio 0
	s_setprio 1
	v_mfma_f32_16x16x32_bf16 v[52:55], v[170:173], v[190:193], v[52:55]
	v_mfma_f32_16x16x32_bf16 v[48:51], v[178:181], v[190:193], v[48:51]
	v_mfma_f32_16x16x32_bf16 v[36:39], v[170:173], v[198:201], v[36:39]
	v_mfma_f32_16x16x32_bf16 v[32:35], v[178:181], v[198:201], v[32:35]
	v_mfma_f32_16x16x32_bf16 v[20:23], v[170:173], v[206:209], v[20:23]
	v_mfma_f32_16x16x32_bf16 v[16:19], v[178:181], v[206:209], v[16:19]
	v_mfma_f32_16x16x32_bf16 v[4:7], v[170:173], v[214:217], v[4:7]
	v_mfma_f32_16x16x32_bf16 v[0:3], v[178:181], v[214:217], v[0:3]
	v_mfma_f32_16x16x32_bf16 v[52:55], v[174:177], v[194:197], v[52:55]
	v_mfma_f32_16x16x32_bf16 v[48:51], v[182:185], v[194:197], v[48:51]
	v_mfma_f32_16x16x32_bf16 v[36:39], v[174:177], v[202:205], v[36:39]
	v_mfma_f32_16x16x32_bf16 v[32:35], v[182:185], v[202:205], v[32:35]
	v_mfma_f32_16x16x32_bf16 v[20:23], v[174:177], v[210:213], v[20:23]
	v_mfma_f32_16x16x32_bf16 v[16:19], v[182:185], v[210:213], v[16:19]
	v_mfma_f32_16x16x32_bf16 v[4:7], v[174:177], v[218:221], v[4:7]
	v_mfma_f32_16x16x32_bf16 v[0:3], v[182:185], v[218:221], v[0:3]
	s_setprio 2
	s_barrier
; #define PG8_STAGE(bufoff, gbase, voff) do { _Pragma("unroll") for (int _i = 0; _i < 2; ++_i) \
;         __builtin_amdgcn_global_load_lds((const unsigned*)((const char*)(gbase) + (voff)[_i]), (LAS unsigned*)(lds + (bufoff) + ldsw + _i * 8192), 16, 0, 0); } while (0)
; #define PG8_LDA(dst, b, h) do { _Pragma("unroll") for (int m = 0; m < 4; ++m) _Pragma("unroll") for (int k = 0; k < 2; ++k) dst[m][k] = *(const LAS bf16x8*)(lds + PG8_SA(b, h) + aoff + m * 2048 + k * 1024); } while (0)
; #define PG8_LDB(dst, b, h) do { _Pragma("unroll") for (int n = 0; n < 2; ++n) _Pragma("unroll") for (int k = 0; k < 2; ++k) dst[n][k] = *(const LAS bf16x8*)(lds + PG8_SB(b, h) + boff + n * 2048 + k * 1024); } while (0)
; #define PG8_MMA(ai, bj, At, Bt) do { __builtin_amdgcn_s_setprio(1); _Pragma("unroll") for (int m = 0; m < 4; ++m) _Pragma("unroll") for (int n = 0; n < 2; ++n) _Pragma("unroll") for (int k = 0; k < 2; ++k) \
;         acc[ai][bj][m][n] = __builtin_amdgcn_mfma_f32_16x16x32_bf16(Bt[n][k], At[m][k], acc[ai][bj][m][n], 0, 0, 0); __builtin_amdgcn_s_setprio(0); } while (0)
; #define PG8_WAIT_V(n) asm volatile("s_waitcnt vmcnt(" #n ")" ::: "memory")
; #define PG8_WAIT_L(n) asm volatile("s_waitcnt lgkmcnt(" #n ")" ::: "memory")
; #define PG8_BAR __builtin_amdgcn_s_barrier()
; #define PG8_SCHED __builtin_amdgcn_sched_barrier(0)
; template <class Epi, class Sched>
; __device__ __forceinline__ void gemm_phase(LAS unsigned char* lds, const Gemm g, const Sched& S, const Epi& E) {
;     ...
;             PG8_LDB(B0, 1, 0); PG8_LDB(B1, 1, 1); PG8_SCHED; PG8_LDA(At, 1, 0); PG8_STAGE(PG8_SA(0, 1), a2 + hstepA, voffA);
;             PG8_WAIT_V(8); PG8_WAIT_L(0); PG8_BAR; PG8_MMA(0, 0, At, B0); PG8_MMA(0, 1, At, B1); PG8_BAR; PG8_SCHED;
;             PG8_LDA(At, 1, 1); PG8_STAGE(PG8_SB(1, 0), b3, voffB); PG8_STAGE(PG8_SB(1, 1), b3 + hstepB, voffB); PG8_STAGE(PG8_SA(1, 0), a3, voffA);
;             PG8_WAIT_V(8); PG8_WAIT_L(0); PG8_BAR; PG8_MMA(1, 0, At, B0); PG8_MMA(1, 1, At, B1); PG8_BAR; PG8_SCHED;
;         }
;         if (wr == 0) PG8_BAR;
	s_add_i32 s46, 0, 0x18000
	s_add_i32 s47, 0, 0x1c000
	v_add_u32_e32 v166, s46, v153
	v_add_u32_e32 v182, s47, v153
	ds_read_b128 v[146:149], v166
	ds_read_b128 v[158:161], v166 offset:1024
	ds_read_b128 v[162:165], v166 offset:2048
	ds_read_b128 v[166:169], v166 offset:3072
	ds_read_b128 v[170:173], v182
	ds_read_b128 v[174:177], v182 offset:1024
	ds_read_b128 v[178:181], v182 offset:2048
	ds_read_b128 v[182:185], v182 offset:3072
	s_add_u32 s2, s60, 0x80000
	s_addc_u32 s3, s61, 0
	s_mov_b32 m0, s64
	ds_read_b128 v[190:193], v156 offset:32768
	ds_read_b128 v[194:197], v156 offset:33792
	ds_read_b128 v[198:201], v156 offset:34816
	ds_read_b128 v[202:205], v156 offset:35840
	ds_read_b128 v[206:209], v156 offset:36864
	ds_read_b128 v[210:213], v156 offset:37888
	ds_read_b128 v[214:217], v156 offset:38912
	ds_read_b128 v[218:221], v156 offset:39936
	global_load_lds_dwordx4 v128, s[2:3]
	s_mov_b32 m0, s65
	s_nop 0
	global_load_lds_dwordx4 v132, s[2:3]
	s_waitcnt vmcnt(8)
	s_waitcnt lgkmcnt(0)
	s_barrier
	s_setprio 1
	s_waitcnt lgkmcnt(0)
	v_mfma_f32_16x16x32_bf16 v[124:127], v[146:149], v[190:193], v[124:127]
	v_mfma_f32_16x16x32_bf16 v[120:123], v[162:165], v[190:193], v[120:123]
	v_mfma_f32_16x16x32_bf16 v[108:111], v[146:149], v[198:201], v[108:111]
	v_mfma_f32_16x16x32_bf16 v[104:107], v[162:165], v[198:201], v[104:107]
	v_mfma_f32_16x16x32_bf16 v[92:95], v[146:149], v[206:209], v[92:95]
	v_mfma_f32_16x16x32_bf16 v[88:91], v[162:165], v[206:209], v[88:91]
	v_mfma_f32_16x16x32_bf16 v[76:79], v[146:149], v[214:217], v[76:79]
	v_mfma_f32_16x16x32_bf16 v[72:75], v[162:165], v[214:217], v[72:75]
	v_mfma_f32_16x16x32_bf16 v[124:127], v[158:161], v[194:197], v[124:127]
	v_mfma_f32_16x16x32_bf16 v[120:123], v[166:169], v[194:197], v[120:123]
	v_mfma_f32_16x16x32_bf16 v[108:111], v[158:161], v[202:205], v[108:111]
	v_mfma_f32_16x16x32_bf16 v[104:107], v[166:169], v[202:205], v[104:107]
	v_mfma_f32_16x16x32_bf16 v[92:95], v[158:161], v[210:213], v[92:95]
	v_mfma_f32_16x16x32_bf16 v[88:91], v[166:169], v[210:213], v[88:91]
	v_mfma_f32_16x16x32_bf16 v[76:79], v[158:161], v[218:221], v[76:79]
	v_mfma_f32_16x16x32_bf16 v[72:75], v[166:169], v[218:221], v[72:75]
	s_setprio 0
	s_setprio 1
	v_mfma_f32_16x16x32_bf16 v[116:119], v[170:173], v[190:193], v[116:119]
	v_mfma_f32_16x16x32_bf16 v[112:115], v[178:181], v[190:193], v[112:115]
	v_mfma_f32_16x16x32_bf16 v[100:103], v[170:173], v[198:201], v[100:103]
	v_mfma_f32_16x16x32_bf16 v[96:99], v[178:181], v[198:201], v[96:99]
	v_mfma_f32_16x16x32_bf16 v[84:87], v[170:173], v[206:209], v[84:87]
	v_mfma_f32_16x16x32_bf16 v[80:83], v[178:181], v[206:209], v[80:83]
	v_mfma_f32_16x16x32_bf16 v[68:71], v[170:173], v[214:217], v[68:71]
	v_mfma_f32_16x16x32_bf16 v[64:67], v[178:181], v[214:217], v[64:67]
	v_mfma_f32_16x16x32_bf16 v[116:119], v[174:177], v[194:197], v[116:119]
	v_mfma_f32_16x16x32_bf16 v[112:115], v[182:185], v[194:197], v[112:115]
	v_mfma_f32_16x16x32_bf16 v[100:103], v[174:177], v[202:205], v[100:103]
	v_mfma_f32_16x16x32_bf16 v[96:99], v[182:185], v[202:205], v[96:99]
	v_mfma_f32_16x16x32_bf16 v[84:87], v[174:177], v[210:213], v[84:87]
	v_mfma_f32_16x16x32_bf16 v[80:83], v[182:185], v[210:213], v[80:83]
	v_mfma_f32_16x16x32_bf16 v[68:71], v[174:177], v[218:221], v[68:71]
	v_mfma_f32_16x16x32_bf16 v[64:67], v[182:185], v[218:221], v[64:67]
	s_setprio 2
	s_barrier
	s_add_i32 s2, s46, s33
	s_add_i32 m0, s2, 0xffffff80
	ds_read_b128 v[190:193], v156 offset:49152
	ds_read_b128 v[194:197], v156 offset:50176
	ds_read_b128 v[198:201], v156 offset:51200
	ds_read_b128 v[202:205], v156 offset:52224
	ds_read_b128 v[206:209], v156 offset:53248
	ds_read_b128 v[210:213], v156 offset:54272
	ds_read_b128 v[214:217], v156 offset:55296
	ds_read_b128 v[218:221], v156 offset:56320
	global_load_lds_dwordx4 v130, s[56:57] offset:128
	s_add_i32 m0, s2, 0x1f80
	s_add_u32 s2, s56, 0x80080
	s_addc_u32 s3, s57, 0
	s_add_i32 s46, s47, s33
	global_load_lds_dwordx4 v134, s[56:57] offset:128
	s_mov_b32 m0, s46
	s_nop 0
	global_load_lds_dwordx4 v130, s[2:3]
	s_add_i32 m0, s46, 0x2000
	s_nop 0
	global_load_lds_dwordx4 v134, s[2:3]
	s_add_i32 m0, s67, 0xffffff80
	s_nop 0
	global_load_lds_dwordx4 v128, s[60:61] offset:128
	s_add_i32 m0, s68, 0xffffff80
	s_nop 0
	global_load_lds_dwordx4 v132, s[60:61] offset:128
	s_waitcnt vmcnt(8)
	s_waitcnt lgkmcnt(0)
	s_barrier
	s_setprio 1
	s_waitcnt lgkmcnt(0)
	v_mfma_f32_16x16x32_bf16 v[60:63], v[146:149], v[190:193], v[60:63]
	v_mfma_f32_16x16x32_bf16 v[56:59], v[162:165], v[190:193], v[56:59]
	v_mfma_f32_16x16x32_bf16 v[44:47], v[146:149], v[198:201], v[44:47]
	v_mfma_f32_16x16x32_bf16 v[40:43], v[162:165], v[198:201], v[40:43]
	v_mfma_f32_16x16x32_bf16 v[28:31], v[146:149], v[206:209], v[28:31]
	v_mfma_f32_16x16x32_bf16 v[24:27], v[162:165], v[206:209], v[24:27]
	v_mfma_f32_16x16x32_bf16 v[12:15], v[146:149], v[214:217], v[12:15]
	v_mfma_f32_16x16x32_bf16 v[8:11], v[162:165], v[214:217], v[8:11]
	v_mfma_f32_16x16x32_bf16 v[60:63], v[158:161], v[194:197], v[60:63]
	v_mfma_f32_16x16x32_bf16 v[56:59], v[166:169], v[194:197], v[56:59]
	v_mfma_f32_16x16x32_bf16 v[44:47], v[158:161], v[202:205], v[44:47]
	v_mfma_f32_16x16x32_bf16 v[40:43], v[166:169], v[202:205], v[40:43]
	v_mfma_f32_16x16x32_bf16 v[28:31], v[158:161], v[210:213], v[28:31]
	v_mfma_f32_16x16x32_bf16 v[24:27], v[166:169], v[210:213], v[24:27]
	v_mfma_f32_16x16x32_bf16 v[12:15], v[158:161], v[218:221], v[12:15]
	v_mfma_f32_16x16x32_bf16 v[8:11], v[166:169], v[218:221], v[8:11]
	s_setprio 0
	s_setprio 1
	v_mfma_f32_16x16x32_bf16 v[52:55], v[170:173], v[190:193], v[52:55]
	v_mfma_f32_16x16x32_bf16 v[48:51], v[178:181], v[190:193], v[48:51]
	v_mfma_f32_16x16x32_bf16 v[36:39], v[170:173], v[198:201], v[36:39]
	v_mfma_f32_16x16x32_bf16 v[32:35], v[178:181], v[198:201], v[32:35]
	v_mfma_f32_16x16x32_bf16 v[20:23], v[170:173], v[206:209], v[20:23]
	v_mfma_f32_16x16x32_bf16 v[16:19], v[178:181], v[206:209], v[16:19]
	v_mfma_f32_16x16x32_bf16 v[4:7], v[170:173], v[214:217], v[4:7]
	v_mfma_f32_16x16x32_bf16 v[0:3], v[178:181], v[214:217], v[0:3]
	v_mfma_f32_16x16x32_bf16 v[52:55], v[174:177], v[194:197], v[52:55]
	v_mfma_f32_16x16x32_bf16 v[48:51], v[182:185], v[194:197], v[48:51]
	v_mfma_f32_16x16x32_bf16 v[36:39], v[174:177], v[202:205], v[36:39]
	v_mfma_f32_16x16x32_bf16 v[32:35], v[182:185], v[202:205], v[32:35]
	v_mfma_f32_16x16x32_bf16 v[20:23], v[174:177], v[210:213], v[20:23]
	v_mfma_f32_16x16x32_bf16 v[16:19], v[182:185], v[210:213], v[16:19]
	v_mfma_f32_16x16x32_bf16 v[4:7], v[174:177], v[218:221], v[4:7]
	v_mfma_f32_16x16x32_bf16 v[0:3], v[182:185], v[218:221], v[0:3]
	s_setprio 2
	s_barrier
	s_add_i32 s77, s77, 2
	s_add_u32 s50, s50, 0x100
	s_addc_u32 s51, s51, 0
	s_add_u32 s39, s39, 0x100
	s_addc_u32 s76, s76, 0
	s_cmp_gt_u32 s77, 29
	s_cbranch_scc0 .LBB0_588
	s_and_b64 vcc, exec, s[16:17]
	s_cbranch_vccz .LBB0_591
	s_barrier

; #define PG8_STAGE(bufoff, gbase, voff) do { _Pragma("unroll") for (int _i = 0; _i < 2; ++_i) \
;         __builtin_amdgcn_global_load_lds((const unsigned*)((const char*)(gbase) + (voff)[_i]), (LAS unsigned*)(lds + (bufoff) + ldsw + _i * 8192), 16, 0, 0); } while (0)
; #define PG8_LDA(dst, b, h) do { _Pragma("unroll") for (int m = 0; m < 4; ++m) _Pragma("unroll") for (int k = 0; k < 2; ++k) dst[m][k] = *(const LAS bf16x8*)(lds + PG8_SA(b, h) + aoff + m * 2048 + k * 1024); } while (0)
; #define PG8_LDB(dst, b, h) do { _Pragma("unroll") for (int n = 0; n < 2; ++n) _Pragma("unroll") for (int k = 0; k < 2; ++k) dst[n][k] = *(const LAS bf16x8*)(lds + PG8_SB(b, h) + boff + n * 2048 + k * 1024); } while (0)
; #define PG8_MMA(ai, bj, At, Bt) do { __builtin_amdgcn_s_setprio(1); _Pragma("unroll") for (int m = 0; m < 4; ++m) _Pragma("unroll") for (int n = 0; n < 2; ++n) _Pragma("unroll") for (int k = 0; k < 2; ++k) \
;         acc[ai][bj][m][n] = __builtin_amdgcn_mfma_f32_16x16x32_bf16(Bt[n][k], At[m][k], acc[ai][bj][m][n], 0, 0, 0); __builtin_amdgcn_s_setprio(0); } while (0)
; #define PG8_WAIT_V(n) asm volatile("s_waitcnt vmcnt(" #n ")" ::: "memory")
; #define PG8_WAIT_L(n) asm volatile("s_waitcnt lgkmcnt(" #n ")" ::: "memory")
; #define PG8_BAR __builtin_amdgcn_s_barrier()
; #define PG8_SCHED __builtin_amdgcn_sched_barrier(0)
; template <class Epi, class Sched>
; __device__ __forceinline__ void gemm_phase(LAS unsigned char* lds, const Gemm g, const Sched& S, const Epi& E) {
;     ...
;         for (int t = 0; t < nt; t += 2) {
;             const bool last = (t == nt - 2);
;             const char* a1 = cA + (size_t)(t + 1) * kstep;
;             const char* a2 = last ? nA : cA + (size_t)(t + 2) * kstep; const char* b2 = last ? nB : cB + (size_t)(t + 2) * kstep;
;             const char* a3 = a2 + kstep; const char* b3 = b2 + kstep;
;             PG8_LDB(B0, 0, 0); PG8_LDB(B1, 0, 1); PG8_SCHED; PG8_LDA(At, 0, 0); PG8_STAGE(PG8_SA(1, 1), a1 + hstepA, voffA);
;             PG8_WAIT_V(8); PG8_WAIT_L(0); PG8_BAR; PG8_MMA(0, 0, At, B0); PG8_MMA(0, 1, At, B1); PG8_BAR; PG8_SCHED;
;             PG8_LDA(At, 0, 1); PG8_STAGE(PG8_SB(0, 0), b2, voffB); PG8_STAGE(PG8_SB(0, 1), b2 + hstepB, voffB); PG8_STAGE(PG8_SA(0, 0), a2, voffA);
;             PG8_WAIT_V(8); PG8_WAIT_L(0); PG8_BAR; PG8_MMA(1, 0, At, B0); PG8_MMA(1, 1, At, B1); PG8_BAR; PG8_SCHED;
.LBB0_883:
	ds_read_b128 v[146:149], v153
	ds_read_b128 v[156:159], v153 offset:1024
	ds_read_b128 v[160:163], v153 offset:2048
	ds_read_b128 v[164:167], v153 offset:3072
	ds_read_b128 v[168:171], v154
	ds_read_b128 v[172:175], v154 offset:1024
	ds_read_b128 v[176:179], v154 offset:2048
	ds_read_b128 v[180:183], v154 offset:3072
	s_add_u32 s2, s38, 0xfff80080
	s_addc_u32 s3, s39, -1
	s_cmp_eq_u32 s61, 28
	s_cselect_b32 s43, s21, s3
	s_cselect_b32 s42, s25, s2
	s_cselect_b32 s41, s57, s60
	s_cselect_b32 s40, s58, s59
	s_add_i32 m0, s37, 0xc000
	ds_read_b128 v[184:187], v155
	ds_read_b128 v[188:191], v155 offset:1024
	ds_read_b128 v[192:195], v155 offset:2048
	ds_read_b128 v[196:199], v155 offset:3072
	ds_read_b128 v[200:203], v155 offset:4096
	ds_read_b128 v[204:207], v155 offset:5120
	ds_read_b128 v[208:211], v155 offset:6144
	ds_read_b128 v[212:215], v155 offset:7168
	global_load_lds_dwordx4 v138, s[38:39]
	s_add_i32 m0, s37, 0xe000
	s_nop 0
	global_load_lds_dwordx4 v140, s[38:39]
	s_waitcnt vmcnt(8)
	s_waitcnt lgkmcnt(0)
	s_barrier
	s_setprio 1
	s_waitcnt lgkmcnt(0)
	v_mfma_f32_16x16x32_bf16 v[124:127], v[146:149], v[184:187], v[124:127]
	v_mfma_f32_16x16x32_bf16 v[120:123], v[160:163], v[184:187], v[120:123]
	v_mfma_f32_16x16x32_bf16 v[108:111], v[146:149], v[192:195], v[108:111]
	v_mfma_f32_16x16x32_bf16 v[104:107], v[160:163], v[192:195], v[104:107]
	v_mfma_f32_16x16x32_bf16 v[92:95], v[146:149], v[200:203], v[92:95]
	v_mfma_f32_16x16x32_bf16 v[88:91], v[160:163], v[200:203], v[88:91]
	v_mfma_f32_16x16x32_bf16 v[76:79], v[146:149], v[208:211], v[76:79]
	v_mfma_f32_16x16x32_bf16 v[72:75], v[160:163], v[208:211], v[72:75]
	v_mfma_f32_16x16x32_bf16 v[124:127], v[156:159], v[188:191], v[124:127]
	v_mfma_f32_16x16x32_bf16 v[120:123], v[164:167], v[188:191], v[120:123]
	v_mfma_f32_16x16x32_bf16 v[108:111], v[156:159], v[196:199], v[108:111]
	v_mfma_f32_16x16x32_bf16 v[104:107], v[164:167], v[196:199], v[104:107]
	v_mfma_f32_16x16x32_bf16 v[92:95], v[156:159], v[204:207], v[92:95]
	v_mfma_f32_16x16x32_bf16 v[88:91], v[164:167], v[204:207], v[88:91]
	v_mfma_f32_16x16x32_bf16 v[76:79], v[156:159], v[212:215], v[76:79]
	v_mfma_f32_16x16x32_bf16 v[72:75], v[164:167], v[212:215], v[72:75]
	s_setprio 0
	s_setprio 1
	v_mfma_f32_16x16x32_bf16 v[116:119], v[168:171], v[184:187], v[116:119]
	v_mfma_f32_16x16x32_bf16 v[112:115], v[176:179], v[184:187], v[112:115]
	v_mfma_f32_16x16x32_bf16 v[100:103], v[168:171], v[192:195], v[100:103]
	v_mfma_f32_16x16x32_bf16 v[96:99], v[176:179], v[192:195], v[96:99]
	v_mfma_f32_16x16x32_bf16 v[84:87], v[168:171], v[200:203], v[84:87]
	v_mfma_f32_16x16x32_bf16 v[80:83], v[176:179], v[200:203], v[80:83]
	v_mfma_f32_16x16x32_bf16 v[68:71], v[168:171], v[208:211], v[68:71]
	v_mfma_f32_16x16x32_bf16 v[64:67], v[176:179], v[208:211], v[64:67]
	v_mfma_f32_16x16x32_bf16 v[116:119], v[172:175], v[188:191], v[116:119]
	v_mfma_f32_16x16x32_bf16 v[112:115], v[180:183], v[188:191], v[112:115]
	v_mfma_f32_16x16x32_bf16 v[100:103], v[172:175], v[196:199], v[100:103]
	v_mfma_f32_16x16x32_bf16 v[96:99], v[180:183], v[196:199], v[96:99]
	v_mfma_f32_16x16x32_bf16 v[84:87], v[172:175], v[204:207], v[84:87]
	v_mfma_f32_16x16x32_bf16 v[80:83], v[180:183], v[204:207], v[80:83]
	v_mfma_f32_16x16x32_bf16 v[68:71], v[172:175], v[212:215], v[68:71]
	v_mfma_f32_16x16x32_bf16 v[64:67], v[180:183], v[212:215], v[64:67]
	s_setprio 2
	s_barrier
	s_add_i32 s2, s54, s47
	s_mov_b32 m0, s2
	ds_read_b128 v[184:187], v155 offset:16384
	ds_read_b128 v[188:191], v155 offset:17408
	ds_read_b128 v[192:195], v155 offset:18432
	ds_read_b128 v[196:199], v155 offset:19456
	ds_read_b128 v[200:203], v155 offset:20480
	ds_read_b128 v[204:207], v155 offset:21504
	ds_read_b128 v[208:211], v155 offset:22528
	ds_read_b128 v[212:215], v155 offset:23552
	global_load_lds_dwordx4 v132, s[40:41]
	s_add_i32 m0, s2, 0x2000
	s_add_u32 s2, s40, 0x80000
	s_addc_u32 s3, s41, 0
	s_add_i32 s22, s55, s47
	global_load_lds_dwordx4 v128, s[40:41]
	s_mov_b32 m0, s22
	s_nop 0
	global_load_lds_dwordx4 v132, s[2:3]
	s_add_i32 m0, s22, 0x2000
	s_nop 0
	global_load_lds_dwordx4 v128, s[2:3]
	s_mov_b32 m0, s37
	s_nop 0
	global_load_lds_dwordx4 v134, s[42:43]
	s_mov_b32 m0, s48
	s_nop 0
	global_load_lds_dwordx4 v130, s[42:43]
	s_waitcnt vmcnt(8)
	s_waitcnt lgkmcnt(0)
	s_barrier
	s_setprio 1
	s_waitcnt lgkmcnt(0)
	v_mfma_f32_16x16x32_bf16 v[60:63], v[146:149], v[184:187], v[60:63]
	v_mfma_f32_16x16x32_bf16 v[56:59], v[160:163], v[184:187], v[56:59]
	v_mfma_f32_16x16x32_bf16 v[44:47], v[146:149], v[192:195], v[44:47]
	v_mfma_f32_16x16x32_bf16 v[40:43], v[160:163], v[192:195], v[40:43]
	v_mfma_f32_16x16x32_bf16 v[28:31], v[146:149], v[200:203], v[28:31]
	v_mfma_f32_16x16x32_bf16 v[24:27], v[160:163], v[200:203], v[24:27]
	v_mfma_f32_16x16x32_bf16 v[12:15], v[146:149], v[208:211], v[12:15]
	v_mfma_f32_16x16x32_bf16 v[8:11], v[160:163], v[208:211], v[8:11]
	v_mfma_f32_16x16x32_bf16 v[60:63], v[156:159], v[188:191], v[60:63]
	v_mfma_f32_16x16x32_bf16 v[56:59], v[164:167], v[188:191], v[56:59]
	v_mfma_f32_16x16x32_bf16 v[44:47], v[156:159], v[196:199], v[44:47]
	v_mfma_f32_16x16x32_bf16 v[40:43], v[164:167], v[196:199], v[40:43]
	v_mfma_f32_16x16x32_bf16 v[28:31], v[156:159], v[204:207], v[28:31]
	v_mfma_f32_16x16x32_bf16 v[24:27], v[164:167], v[204:207], v[24:27]
	v_mfma_f32_16x16x32_bf16 v[12:15], v[156:159], v[212:215], v[12:15]
	v_mfma_f32_16x16x32_bf16 v[8:11], v[164:167], v[212:215], v[8:11]
	s_setprio 0
	s_setprio 1
	v_mfma_f32_16x16x32_bf16 v[52:55], v[168:171], v[184:187], v[52:55]
	v_mfma_f32_16x16x32_bf16 v[48:51], v[176:179], v[184:187], v[48:51]
	v_mfma_f32_16x16x32_bf16 v[36:39], v[168:171], v[192:195], v[36:39]
	v_mfma_f32_16x16x32_bf16 v[32:35], v[176:179], v[192:195], v[32:35]
	v_mfma_f32_16x16x32_bf16 v[20:23], v[168:171], v[200:203], v[20:23]
	v_mfma_f32_16x16x32_bf16 v[16:19], v[176:179], v[200:203], v[16:19]
	v_mfma_f32_16x16x32_bf16 v[4:7], v[168:171], v[208:211], v[4:7]
	v_mfma_f32_16x16x32_bf16 v[0:3], v[176:179], v[208:211], v[0:3]
	v_mfma_f32_16x16x32_bf16 v[52:55], v[172:175], v[188:191], v[52:55]
	v_mfma_f32_16x16x32_bf16 v[48:51], v[180:183], v[188:191], v[48:51]
	v_mfma_f32_16x16x32_bf16 v[36:39], v[172:175], v[196:199], v[36:39]
	v_mfma_f32_16x16x32_bf16 v[32:35], v[180:183], v[196:199], v[32:35]
	v_mfma_f32_16x16x32_bf16 v[20:23], v[172:175], v[204:207], v[20:23]
	v_mfma_f32_16x16x32_bf16 v[16:19], v[180:183], v[204:207], v[16:19]
	v_mfma_f32_16x16x32_bf16 v[4:7], v[172:175], v[212:215], v[4:7]
	v_mfma_f32_16x16x32_bf16 v[0:3], v[180:183], v[212:215], v[0:3]
	s_setprio 2
	s_barrier
; #define PG8_STAGE(bufoff, gbase, voff) do { _Pragma("unroll") for (int _i = 0; _i < 2; ++_i) \
;         __builtin_amdgcn_global_load_lds((const unsigned*)((const char*)(gbase) + (voff)[_i]), (LAS unsigned*)(lds + (bufoff) + ldsw + _i * 8192), 16, 0, 0); } while (0)
; #define PG8_LDA(dst, b, h) do { _Pragma("unroll") for (int m = 0; m < 4; ++m) _Pragma("unroll") for (int k = 0; k < 2; ++k) dst[m][k] = *(const LAS bf16x8*)(lds + PG8_SA(b, h) + aoff + m * 2048 + k * 1024); } while (0)
; #define PG8_LDB(dst, b, h) do { _Pragma("unroll") for (int n = 0; n < 2; ++n) _Pragma("unroll") for (int k = 0; k < 2; ++k) dst[n][k] = *(const LAS bf16x8*)(lds + PG8_SB(b, h) + boff + n * 2048 + k * 1024); } while (0)
; #define PG8_MMA(ai, bj, At, Bt) do { __builtin_amdgcn_s_setprio(1); _Pragma("unroll") for (int m = 0; m < 4; ++m) _Pragma("unroll") for (int n = 0; n < 2; ++n) _Pragma("unroll") for (int k = 0; k < 2; ++k) \
;         acc[ai][bj][m][n] = __builtin_amdgcn_mfma_f32_16x16x32_bf16(Bt[n][k], At[m][k], acc[ai][bj][m][n], 0, 0, 0); __builtin_amdgcn_s_setprio(0); } while (0)
; #define PG8_WAIT_V(n) asm volatile("s_waitcnt vmcnt(" #n ")" ::: "memory")
; #define PG8_WAIT_L(n) asm volatile("s_waitcnt lgkmcnt(" #n ")" ::: "memory")
; #define PG8_BAR __builtin_amdgcn_s_barrier()
; #define PG8_SCHED __builtin_amdgcn_sched_barrier(0)
; template <class Epi, class Sched>
; __device__ __forceinline__ void gemm_phase(LAS unsigned char* lds, const Gemm g, const Sched& S, const Epi& E) {
;     ...
;             PG8_LDB(B0, 1, 0); PG8_LDB(B1, 1, 1); PG8_SCHED; PG8_LDA(At, 1, 0); PG8_STAGE(PG8_SA(0, 1), a2 + hstepA, voffA);
;             PG8_WAIT_V(8); PG8_WAIT_L(0); PG8_BAR; PG8_MMA(0, 0, At, B0); PG8_MMA(0, 1, At, B1); PG8_BAR; PG8_SCHED;
;             PG8_LDA(At, 1, 1); PG8_STAGE(PG8_SB(1, 0), b3, voffB); PG8_STAGE(PG8_SB(1, 1), b3 + hstepB, voffB); PG8_STAGE(PG8_SA(1, 0), a3, voffA);
;             PG8_WAIT_V(8); PG8_WAIT_L(0); PG8_BAR; PG8_MMA(1, 0, At, B0); PG8_MMA(1, 1, At, B1); PG8_BAR; PG8_SCHED;
;         }
;         if (wr == 0) PG8_BAR;
	s_add_i32 s22, 0, 0x18000
	s_add_i32 s23, 0, 0x1c000
	v_add_u32_e32 v164, s22, v152
	v_add_u32_e32 v180, s23, v152
	ds_read_b128 v[146:149], v164
	ds_read_b128 v[156:159], v164 offset:1024
	ds_read_b128 v[160:163], v164 offset:2048
	ds_read_b128 v[164:167], v164 offset:3072
	ds_read_b128 v[168:171], v180
	ds_read_b128 v[172:175], v180 offset:1024
	ds_read_b128 v[176:179], v180 offset:2048
	ds_read_b128 v[180:183], v180 offset:3072
	s_add_u32 s2, s42, 0x80000
	s_addc_u32 s3, s43, 0
	s_mov_b32 m0, s49
	ds_read_b128 v[184:187], v155 offset:32768
	ds_read_b128 v[188:191], v155 offset:33792
	ds_read_b128 v[192:195], v155 offset:34816
	ds_read_b128 v[196:199], v155 offset:35840
	ds_read_b128 v[200:203], v155 offset:36864
	ds_read_b128 v[204:207], v155 offset:37888
	ds_read_b128 v[208:211], v155 offset:38912
	ds_read_b128 v[212:215], v155 offset:39936
	global_load_lds_dwordx4 v134, s[2:3]
	s_mov_b32 m0, s50
	s_nop 0
	global_load_lds_dwordx4 v130, s[2:3]
	s_waitcnt vmcnt(8)
	s_waitcnt lgkmcnt(0)
	s_barrier
	s_setprio 1
	s_waitcnt lgkmcnt(0)
	v_mfma_f32_16x16x32_bf16 v[124:127], v[146:149], v[184:187], v[124:127]
	v_mfma_f32_16x16x32_bf16 v[120:123], v[160:163], v[184:187], v[120:123]
	v_mfma_f32_16x16x32_bf16 v[108:111], v[146:149], v[192:195], v[108:111]
	v_mfma_f32_16x16x32_bf16 v[104:107], v[160:163], v[192:195], v[104:107]
	v_mfma_f32_16x16x32_bf16 v[92:95], v[146:149], v[200:203], v[92:95]
	v_mfma_f32_16x16x32_bf16 v[88:91], v[160:163], v[200:203], v[88:91]
	v_mfma_f32_16x16x32_bf16 v[76:79], v[146:149], v[208:211], v[76:79]
	v_mfma_f32_16x16x32_bf16 v[72:75], v[160:163], v[208:211], v[72:75]
	v_mfma_f32_16x16x32_bf16 v[124:127], v[156:159], v[188:191], v[124:127]
	v_mfma_f32_16x16x32_bf16 v[120:123], v[164:167], v[188:191], v[120:123]
	v_mfma_f32_16x16x32_bf16 v[108:111], v[156:159], v[196:199], v[108:111]
	v_mfma_f32_16x16x32_bf16 v[104:107], v[164:167], v[196:199], v[104:107]
	v_mfma_f32_16x16x32_bf16 v[92:95], v[156:159], v[204:207], v[92:95]
	v_mfma_f32_16x16x32_bf16 v[88:91], v[164:167], v[204:207], v[88:91]
	v_mfma_f32_16x16x32_bf16 v[76:79], v[156:159], v[212:215], v[76:79]
	v_mfma_f32_16x16x32_bf16 v[72:75], v[164:167], v[212:215], v[72:75]
	s_setprio 0
	s_setprio 1
	v_mfma_f32_16x16x32_bf16 v[116:119], v[168:171], v[184:187], v[116:119]
	v_mfma_f32_16x16x32_bf16 v[112:115], v[176:179], v[184:187], v[112:115]
	v_mfma_f32_16x16x32_bf16 v[100:103], v[168:171], v[192:195], v[100:103]
	v_mfma_f32_16x16x32_bf16 v[96:99], v[176:179], v[192:195], v[96:99]
	v_mfma_f32_16x16x32_bf16 v[84:87], v[168:171], v[200:203], v[84:87]
	v_mfma_f32_16x16x32_bf16 v[80:83], v[176:179], v[200:203], v[80:83]
	v_mfma_f32_16x16x32_bf16 v[68:71], v[168:171], v[208:211], v[68:71]
	v_mfma_f32_16x16x32_bf16 v[64:67], v[176:179], v[208:211], v[64:67]
	v_mfma_f32_16x16x32_bf16 v[116:119], v[172:175], v[188:191], v[116:119]
	v_mfma_f32_16x16x32_bf16 v[112:115], v[180:183], v[188:191], v[112:115]
	v_mfma_f32_16x16x32_bf16 v[100:103], v[172:175], v[196:199], v[100:103]
	v_mfma_f32_16x16x32_bf16 v[96:99], v[180:183], v[196:199], v[96:99]
	v_mfma_f32_16x16x32_bf16 v[84:87], v[172:175], v[204:207], v[84:87]
	v_mfma_f32_16x16x32_bf16 v[80:83], v[180:183], v[204:207], v[80:83]
	v_mfma_f32_16x16x32_bf16 v[68:71], v[172:175], v[212:215], v[68:71]
	v_mfma_f32_16x16x32_bf16 v[64:67], v[180:183], v[212:215], v[64:67]
	s_setprio 2
	s_barrier
	s_add_i32 s2, s22, s47
	s_add_i32 m0, s2, 0xffffff80
	ds_read_b128 v[184:187], v155 offset:49152
	ds_read_b128 v[188:191], v155 offset:50176
	ds_read_b128 v[192:195], v155 offset:51200
	ds_read_b128 v[196:199], v155 offset:52224
	ds_read_b128 v[200:203], v155 offset:53248
	ds_read_b128 v[204:207], v155 offset:54272
	ds_read_b128 v[208:211], v155 offset:55296
	ds_read_b128 v[212:215], v155 offset:56320
	global_load_lds_dwordx4 v132, s[40:41] offset:128
	s_add_i32 m0, s2, 0x1f80
	s_add_u32 s2, s40, 0x80080
	s_addc_u32 s3, s41, 0
	s_add_i32 s22, s23, s47
	global_load_lds_dwordx4 v128, s[40:41] offset:128
	s_mov_b32 m0, s22
	s_nop 0
	global_load_lds_dwordx4 v132, s[2:3]
	s_add_i32 m0, s22, 0x2000
	s_nop 0
	global_load_lds_dwordx4 v128, s[2:3]
	s_add_i32 m0, s52, 0xffffff80
	s_nop 0
	global_load_lds_dwordx4 v134, s[42:43] offset:128
	s_add_i32 m0, s53, 0xffffff80
	s_nop 0
	global_load_lds_dwordx4 v130, s[42:43] offset:128
	s_waitcnt vmcnt(8)
	s_waitcnt lgkmcnt(0)
	s_barrier
	s_setprio 1
	s_waitcnt lgkmcnt(0)
	v_mfma_f32_16x16x32_bf16 v[60:63], v[146:149], v[184:187], v[60:63]
	v_mfma_f32_16x16x32_bf16 v[56:59], v[160:163], v[184:187], v[56:59]
	v_mfma_f32_16x16x32_bf16 v[44:47], v[146:149], v[192:195], v[44:47]
	v_mfma_f32_16x16x32_bf16 v[40:43], v[160:163], v[192:195], v[40:43]
	v_mfma_f32_16x16x32_bf16 v[28:31], v[146:149], v[200:203], v[28:31]
	v_mfma_f32_16x16x32_bf16 v[24:27], v[160:163], v[200:203], v[24:27]
	v_mfma_f32_16x16x32_bf16 v[12:15], v[146:149], v[208:211], v[12:15]
	v_mfma_f32_16x16x32_bf16 v[8:11], v[160:163], v[208:211], v[8:11]
	v_mfma_f32_16x16x32_bf16 v[60:63], v[156:159], v[188:191], v[60:63]
	v_mfma_f32_16x16x32_bf16 v[56:59], v[164:167], v[188:191], v[56:59]
	v_mfma_f32_16x16x32_bf16 v[44:47], v[156:159], v[196:199], v[44:47]
	v_mfma_f32_16x16x32_bf16 v[40:43], v[164:167], v[196:199], v[40:43]
	v_mfma_f32_16x16x32_bf16 v[28:31], v[156:159], v[204:207], v[28:31]
	v_mfma_f32_16x16x32_bf16 v[24:27], v[164:167], v[204:207], v[24:27]
	v_mfma_f32_16x16x32_bf16 v[12:15], v[156:159], v[212:215], v[12:15]
	v_mfma_f32_16x16x32_bf16 v[8:11], v[164:167], v[212:215], v[8:11]
	s_setprio 0
	s_setprio 1
	v_mfma_f32_16x16x32_bf16 v[52:55], v[168:171], v[184:187], v[52:55]
	v_mfma_f32_16x16x32_bf16 v[48:51], v[176:179], v[184:187], v[48:51]
	v_mfma_f32_16x16x32_bf16 v[36:39], v[168:171], v[192:195], v[36:39]
	v_mfma_f32_16x16x32_bf16 v[32:35], v[176:179], v[192:195], v[32:35]
	v_mfma_f32_16x16x32_bf16 v[20:23], v[168:171], v[200:203], v[20:23]
	v_mfma_f32_16x16x32_bf16 v[16:19], v[176:179], v[200:203], v[16:19]
	v_mfma_f32_16x16x32_bf16 v[4:7], v[168:171], v[208:211], v[4:7]
	v_mfma_f32_16x16x32_bf16 v[0:3], v[176:179], v[208:211], v[0:3]
	v_mfma_f32_16x16x32_bf16 v[52:55], v[172:175], v[188:191], v[52:55]
	v_mfma_f32_16x16x32_bf16 v[48:51], v[180:183], v[188:191], v[48:51]
	v_mfma_f32_16x16x32_bf16 v[36:39], v[172:175], v[196:199], v[36:39]
	v_mfma_f32_16x16x32_bf16 v[32:35], v[180:183], v[196:199], v[32:35]
	v_mfma_f32_16x16x32_bf16 v[20:23], v[172:175], v[204:207], v[20:23]
	v_mfma_f32_16x16x32_bf16 v[16:19], v[180:183], v[204:207], v[16:19]
	v_mfma_f32_16x16x32_bf16 v[4:7], v[172:175], v[212:215], v[4:7]
	v_mfma_f32_16x16x32_bf16 v[0:3], v[180:183], v[212:215], v[0:3]
	s_setprio 2
	s_barrier
	s_add_i32 s61, s61, 2
	s_add_u32 s38, s38, 0x100
	s_addc_u32 s39, s39, 0
	s_add_u32 s59, s59, 0x100
	s_addc_u32 s60, s60, 0
	s_cmp_gt_u32 s61, 29
	s_cbranch_scc0 .LBB0_883
	s_and_b64 vcc, exec, s[10:11]
	s_cbranch_vccz .LBB0_886
	s_barrier
